# start-up cooperative-groups grid sync removed (XCD barrier census already waits for every workgroup)
# speedup vs baseline: 1.0012x; 1.0012x over previous
.LBB0_5:
	s_or_b64 exec, exec, s[6:7]
	v_lshrrev_b32_e32 v1, 20, v0
	v_lshrrev_b32_e32 v0, 10, v0
	v_or_b32_e32 v0, v0, v1
	s_movk_i32 s0, 0x3ff
	v_and_or_b32 v0, v0, s0, v135
	v_cmp_eq_u32_e32 vcc, 0, v0
	s_barrier
	s_mov_b64 s[6:7], exec
